# v76 + grid barrier: all workgroups wait on the cross-XCD release word directly, per-XCD relay atomic removed (one memory round trip less per barrier release)
# speedup vs baseline: 1.0017x; 1.0017x over previous
; __device__ __forceinline__ unsigned xb_ld(unsigned* p)              { return __hip_atomic_load(p, __ATOMIC_RELAXED, __HIP_MEMORY_SCOPE_AGENT); }
; __device__ __forceinline__ unsigned xb_add(unsigned* p, unsigned v) { return __hip_atomic_fetch_add(p, v, __ATOMIC_RELAXED, __HIP_MEMORY_SCOPE_AGENT); }
; #define XB_SPIN(cond, bar) do { unsigned _sp = 0; while (cond) { __builtin_amdgcn_s_sleep(1); \
;     if ((++_sp & 255u) == 0u) { if (xb_ld(&(bar)[XB_TMO])) break; if (_sp > XB_SPIN_CAP) { atomicAdd(&(bar)[XB_TMO], 1u); break; } } } } while (0)
; __device__ __forceinline__ void xcd_barrier(const XcdBarrier& b) {
;     ...
;         const unsigned old = xb_add(&bar[XB_XSUB(bx_)], 1u);
;         const unsigned gen = old / nloc;
;         if (old + 1u == (gen + 1u) * nloc) {
;             __builtin_amdgcn_fence(__ATOMIC_RELEASE, "agent");
;             asm volatile("s_waitcnt vmcnt(0)" ::: "memory");
;             const unsigned og = xb_add(&bar[XB_TOP], 1u);
;             const unsigned tg = og / nx;
;             if (og + 1u == (tg + 1u) * nx) xb_add(&bar[XB_TOPGEN], 1u);
;             else XB_SPIN(xb_ld(&bar[XB_TOPGEN]) == tg, bar);
;             __builtin_amdgcn_fence(__ATOMIC_ACQUIRE, "agent");
;             xb_add(&bar[XB_XGEN(bx_)], 1u);
;             asm volatile("s_waitcnt vmcnt(0)" ::: "memory");
;         } else {
;             XB_SPIN(xb_ld(&bar[XB_XGEN(bx_)]) == gen, bar);
.LBB0_146:
	s_or_b64 exec, exec, s[10:11]
	v_cvt_f32_u32_e32 v5, v3
	s_waitcnt vmcnt(0)
	v_readfirstlane_b32 s1, v4
	v_sub_u32_e32 v4, 0, v3
	v_rcp_iflag_f32_e32 v5, v5
	v_add_u32_e32 v6, s1, v2
	v_mul_f32_e32 v5, 0x4f7ffffe, v5
	v_cvt_u32_f32_e32 v5, v5
	v_mul_lo_u32 v2, v4, v5
	v_mul_hi_u32 v2, v5, v2
	v_add_u32_e32 v2, v5, v2
	v_mul_hi_u32 v2, v6, v2
	v_mul_lo_u32 v4, v2, v3
	v_sub_u32_e32 v4, v6, v4
	v_add_u32_e32 v5, 1, v2
	v_cmp_ge_u32_e32 vcc, v4, v3
	s_nop 1
	v_cndmask_b32_e32 v2, v2, v5, vcc
	v_sub_u32_e32 v5, v4, v3
	v_cndmask_b32_e32 v4, v4, v5, vcc
	v_add_u32_e32 v5, 1, v2
	v_cmp_ge_u32_e32 vcc, v4, v3
	v_add_u32_e32 v4, 1, v6
	s_nop 0
	v_cndmask_b32_e32 v2, v2, v5, vcc
	v_mul_lo_u32 v5, v3, v2
	v_add_u32_e32 v3, v5, v3
	v_cmp_ne_u32_e32 vcc, v4, v3
	s_and_saveexec_b64 s[8:9], vcc
	s_xor_b64 s[8:9], exec, s[8:9]
	s_cbranch_execz .LBB0_160
	s_add_i32 s10, s0, 0x900
	s_mov_b32 s11, 0
	s_lshl_b64 s[10:11], s[10:11], 2
	s_add_u32 s12, s6, 0x3500
	s_addc_u32 s13, s7, 0
	s_waitcnt lgkmcnt(0)
	v_mov_b32_e32 v1, 0
	global_load_dword v3, v1, s[12:13] sc1
	s_waitcnt vmcnt(0)
	v_cmp_eq_u32_e32 vcc, v3, v2
	s_and_saveexec_b64 s[10:11], vcc
	s_cbranch_execz .LBB0_159
	s_mov_b32 s1, 1
	s_mov_b64 s[14:15], 0
	s_branch .LBB0_150

; __device__ __forceinline__ unsigned xb_add(unsigned* p, unsigned v) { return __hip_atomic_fetch_add(p, v, __ATOMIC_RELAXED, __HIP_MEMORY_SCOPE_AGENT); }
; __device__ __forceinline__ void xcd_barrier(const XcdBarrier& b) {
;     ...
;             __builtin_amdgcn_fence(__ATOMIC_ACQUIRE, "agent");
;             xb_add(&bar[XB_XGEN(bx_)], 1u);
;             asm volatile("s_waitcnt vmcnt(0)" ::: "memory");
.LBB0_177:
	s_or_b64 exec, exec, s[8:9]
	s_mov_b64 s[8:9], exec
	v_mbcnt_lo_u32_b32 v1, s8, 0
	v_mbcnt_hi_u32_b32 v1, s9, v1
	s_mov_b32 s13, 0
	v_cmp_eq_u32_e32 vcc, 0, v1
	s_waitcnt vmcnt(0)
	buffer_inv sc1
	s_and_saveexec_b64 s[10:11], vcc
	s_cbranch_execz .LBB0_179
	s_add_i32 s12, s0, 0x900
	s_lshl_b64 s[0:1], s[12:13], 2
	s_add_u32 s0, s6, s0
	s_addc_u32 s1, s7, s1
	s_bcnt1_i32_b64 s6, s[8:9]
	v_mov_b32_e32 v1, 0
	v_mov_b32_e32 v2, s6
.LBB0_179:
	s_or_b64 exec, exec, s[10:11]
	s_waitcnt vmcnt(0)

; __device__ __forceinline__ unsigned xb_ld(unsigned* p)              { return __hip_atomic_load(p, __ATOMIC_RELAXED, __HIP_MEMORY_SCOPE_AGENT); }
; __device__ __forceinline__ unsigned xb_add(unsigned* p, unsigned v) { return __hip_atomic_fetch_add(p, v, __ATOMIC_RELAXED, __HIP_MEMORY_SCOPE_AGENT); }
; #define XB_SPIN(cond, bar) do { unsigned _sp = 0; while (cond) { __builtin_amdgcn_s_sleep(1); \
;     if ((++_sp & 255u) == 0u) { if (xb_ld(&(bar)[XB_TMO])) break; if (_sp > XB_SPIN_CAP) { atomicAdd(&(bar)[XB_TMO], 1u); break; } } } } while (0)
; __device__ __forceinline__ void xcd_barrier(const XcdBarrier& b) {
;     ...
;         const unsigned old = xb_add(&bar[XB_XSUB(bx_)], 1u);
;         const unsigned gen = old / nloc;
;         if (old + 1u == (gen + 1u) * nloc) {
;             __builtin_amdgcn_fence(__ATOMIC_RELEASE, "agent");
;             asm volatile("s_waitcnt vmcnt(0)" ::: "memory");
;             const unsigned og = xb_add(&bar[XB_TOP], 1u);
;             const unsigned tg = og / nx;
;             if (og + 1u == (tg + 1u) * nx) xb_add(&bar[XB_TOPGEN], 1u);
;             else XB_SPIN(xb_ld(&bar[XB_TOPGEN]) == tg, bar);
;             __builtin_amdgcn_fence(__ATOMIC_ACQUIRE, "agent");
;             xb_add(&bar[XB_XGEN(bx_)], 1u);
;             asm volatile("s_waitcnt vmcnt(0)" ::: "memory");
;         } else {
;             XB_SPIN(xb_ld(&bar[XB_XGEN(bx_)]) == gen, bar);
.LBB0_239:
	s_or_b64 exec, exec, s[14:15]
	v_cvt_f32_u32_e32 v7, v5
	s_waitcnt vmcnt(0)
	v_readfirstlane_b32 s12, v6
	v_sub_u32_e32 v6, 0, v5
	v_rcp_iflag_f32_e32 v7, v7
	v_add_u32_e32 v8, s12, v3
	v_mul_f32_e32 v7, 0x4f7ffffe, v7
	v_cvt_u32_f32_e32 v7, v7
	v_mul_lo_u32 v3, v6, v7
	v_mul_hi_u32 v3, v7, v3
	v_add_u32_e32 v3, v7, v3
	v_mul_hi_u32 v3, v8, v3
	v_mul_lo_u32 v6, v3, v5
	v_sub_u32_e32 v6, v8, v6
	v_add_u32_e32 v7, 1, v3
	v_cmp_ge_u32_e32 vcc, v6, v5
	s_nop 1
	v_cndmask_b32_e32 v3, v3, v7, vcc
	v_sub_u32_e32 v7, v6, v5
	v_cndmask_b32_e32 v6, v6, v7, vcc
	v_add_u32_e32 v7, 1, v3
	v_cmp_ge_u32_e32 vcc, v6, v5
	v_add_u32_e32 v6, 1, v8
	s_nop 0
	v_cndmask_b32_e32 v3, v3, v7, vcc
	v_mul_lo_u32 v7, v5, v3
	v_add_u32_e32 v5, v7, v5
	v_cmp_ne_u32_e32 vcc, v6, v5
	s_and_saveexec_b64 s[12:13], vcc
	s_xor_b64 s[12:13], exec, s[12:13]
	s_cbranch_execz .LBB0_253
	s_add_i32 s44, s1, 0x900
	s_lshl_b64 s[14:15], s[44:45], 2
	s_add_u32 s24, s10, 0x3500
	s_addc_u32 s25, s11, 0
	s_waitcnt lgkmcnt(0)
	global_load_dword v4, v201, s[24:25] sc1
	s_waitcnt vmcnt(0)
	v_cmp_eq_u32_e32 vcc, v4, v3
	s_and_saveexec_b64 s[14:15], vcc
	s_cbranch_execz .LBB0_252
	s_mov_b32 s20, 1
	s_mov_b64 s[50:51], 0
	s_branch .LBB0_243

; __device__ __forceinline__ unsigned xb_add(unsigned* p, unsigned v) { return __hip_atomic_fetch_add(p, v, __ATOMIC_RELAXED, __HIP_MEMORY_SCOPE_AGENT); }
; __device__ __forceinline__ void xcd_barrier(const XcdBarrier& b) {
;     ...
;             __builtin_amdgcn_fence(__ATOMIC_ACQUIRE, "agent");
;             xb_add(&bar[XB_XGEN(bx_)], 1u);
;             asm volatile("s_waitcnt vmcnt(0)" ::: "memory");
.LBB0_270:
	s_or_b64 exec, exec, s[12:13]
	s_mov_b64 s[12:13], exec
	v_mbcnt_lo_u32_b32 v3, s12, 0
	v_mbcnt_hi_u32_b32 v3, s13, v3
	v_cmp_eq_u32_e32 vcc, 0, v3
	s_waitcnt vmcnt(0)
	buffer_inv sc1
	s_and_saveexec_b64 s[14:15], vcc
	s_cbranch_execz .LBB0_272
	s_add_i32 s44, s1, 0x900
	s_lshl_b64 s[20:21], s[44:45], 2
	s_add_u32 s10, s10, s20
	s_addc_u32 s11, s11, s21
	s_bcnt1_i32_b64 s1, s[12:13]
	v_mov_b32_e32 v3, s1
.LBB0_272:
	s_or_b64 exec, exec, s[14:15]
	s_waitcnt vmcnt(0)

; __device__ __forceinline__ unsigned xb_ld(unsigned* p)              { return __hip_atomic_load(p, __ATOMIC_RELAXED, __HIP_MEMORY_SCOPE_AGENT); }
; __device__ __forceinline__ unsigned xb_add(unsigned* p, unsigned v) { return __hip_atomic_fetch_add(p, v, __ATOMIC_RELAXED, __HIP_MEMORY_SCOPE_AGENT); }
; #define XB_SPIN(cond, bar) do { unsigned _sp = 0; while (cond) { __builtin_amdgcn_s_sleep(1); \
;     if ((++_sp & 255u) == 0u) { if (xb_ld(&(bar)[XB_TMO])) break; if (_sp > XB_SPIN_CAP) { atomicAdd(&(bar)[XB_TMO], 1u); break; } } } } while (0)
; __device__ __forceinline__ void xcd_barrier(const XcdBarrier& b) {
;     ...
;         const unsigned old = xb_add(&bar[XB_XSUB(bx_)], 1u);
;         const unsigned gen = old / nloc;
;         if (old + 1u == (gen + 1u) * nloc) {
;             __builtin_amdgcn_fence(__ATOMIC_RELEASE, "agent");
;             asm volatile("s_waitcnt vmcnt(0)" ::: "memory");
;             const unsigned og = xb_add(&bar[XB_TOP], 1u);
;             const unsigned tg = og / nx;
;             if (og + 1u == (tg + 1u) * nx) xb_add(&bar[XB_TOPGEN], 1u);
;             else XB_SPIN(xb_ld(&bar[XB_TOPGEN]) == tg, bar);
;             __builtin_amdgcn_fence(__ATOMIC_ACQUIRE, "agent");
;             xb_add(&bar[XB_XGEN(bx_)], 1u);
;             asm volatile("s_waitcnt vmcnt(0)" ::: "memory");
;         } else {
;             XB_SPIN(xb_ld(&bar[XB_XGEN(bx_)]) == gen, bar);
.LBB0_327:
	s_or_b64 exec, exec, s[24:25]
	v_cvt_f32_u32_e32 v7, v5
	s_waitcnt vmcnt(0)
	v_readfirstlane_b32 s1, v6
	v_sub_u32_e32 v6, 0, v5
	v_rcp_iflag_f32_e32 v7, v7
	v_add_u32_e32 v8, s1, v3
	v_mul_f32_e32 v7, 0x4f7ffffe, v7
	v_cvt_u32_f32_e32 v7, v7
	v_mul_lo_u32 v3, v6, v7
	v_mul_hi_u32 v3, v7, v3
	v_add_u32_e32 v3, v7, v3
	v_mul_hi_u32 v3, v8, v3
	v_mul_lo_u32 v6, v3, v5
	v_sub_u32_e32 v6, v8, v6
	v_add_u32_e32 v7, 1, v3
	v_cmp_ge_u32_e32 vcc, v6, v5
	s_nop 1
	v_cndmask_b32_e32 v3, v3, v7, vcc
	v_sub_u32_e32 v7, v6, v5
	v_cndmask_b32_e32 v6, v6, v7, vcc
	v_add_u32_e32 v7, 1, v3
	v_cmp_ge_u32_e32 vcc, v6, v5
	v_add_u32_e32 v6, 1, v8
	s_nop 0
	v_cndmask_b32_e32 v3, v3, v7, vcc
	v_mul_lo_u32 v7, v5, v3
	v_add_u32_e32 v5, v7, v5
	v_cmp_ne_u32_e32 vcc, v6, v5
	s_and_saveexec_b64 s[14:15], vcc
	s_xor_b64 s[14:15], exec, s[14:15]
	s_cbranch_execz .LBB0_341
	s_add_i32 s44, s0, 0x900
	s_lshl_b64 s[20:21], s[44:45], 2
	s_add_u32 s50, s6, 0x3500
	s_addc_u32 s51, s7, 0
	s_waitcnt lgkmcnt(0)
	global_load_dword v4, v201, s[50:51] sc1
	s_waitcnt vmcnt(0)
	v_cmp_eq_u32_e32 vcc, v4, v3
	s_and_saveexec_b64 s[24:25], vcc
	s_cbranch_execz .LBB0_340
	s_mov_b32 s1, 1
	s_mov_b64 s[60:61], 0
	s_branch .LBB0_331

; __device__ __forceinline__ unsigned xb_add(unsigned* p, unsigned v) { return __hip_atomic_fetch_add(p, v, __ATOMIC_RELAXED, __HIP_MEMORY_SCOPE_AGENT); }
; __device__ __forceinline__ void xcd_barrier(const XcdBarrier& b) {
;     ...
;             __builtin_amdgcn_fence(__ATOMIC_ACQUIRE, "agent");
;             xb_add(&bar[XB_XGEN(bx_)], 1u);
;             asm volatile("s_waitcnt vmcnt(0)" ::: "memory");
.LBB0_358:
	s_or_b64 exec, exec, s[14:15]
	s_mov_b64 s[14:15], exec
	v_mbcnt_lo_u32_b32 v3, s14, 0
	v_mbcnt_hi_u32_b32 v3, s15, v3
	v_cmp_eq_u32_e32 vcc, 0, v3
	s_waitcnt vmcnt(0)
	buffer_inv sc1
	s_and_saveexec_b64 s[24:25], vcc
	s_cbranch_execz .LBB0_360
	s_add_i32 s44, s0, 0x900
	s_lshl_b64 s[0:1], s[44:45], 2
	s_add_u32 s0, s6, s0
	s_addc_u32 s1, s7, s1
	s_bcnt1_i32_b64 s6, s[14:15]
	v_mov_b32_e32 v3, s6
.LBB0_360:
	s_or_b64 exec, exec, s[24:25]
	s_waitcnt vmcnt(0)

; __device__ __forceinline__ unsigned xb_ld(unsigned* p)              { return __hip_atomic_load(p, __ATOMIC_RELAXED, __HIP_MEMORY_SCOPE_AGENT); }
; __device__ __forceinline__ unsigned xb_add(unsigned* p, unsigned v) { return __hip_atomic_fetch_add(p, v, __ATOMIC_RELAXED, __HIP_MEMORY_SCOPE_AGENT); }
; #define XB_SPIN(cond, bar) do { unsigned _sp = 0; while (cond) { __builtin_amdgcn_s_sleep(1); \
;     if ((++_sp & 255u) == 0u) { if (xb_ld(&(bar)[XB_TMO])) break; if (_sp > XB_SPIN_CAP) { atomicAdd(&(bar)[XB_TMO], 1u); break; } } } } while (0)
; __device__ __forceinline__ void xcd_barrier(const XcdBarrier& b) {
;     ...
;         const unsigned old = xb_add(&bar[XB_XSUB(bx_)], 1u);
;         const unsigned gen = old / nloc;
;         if (old + 1u == (gen + 1u) * nloc) {
;             __builtin_amdgcn_fence(__ATOMIC_RELEASE, "agent");
;             asm volatile("s_waitcnt vmcnt(0)" ::: "memory");
;             const unsigned og = xb_add(&bar[XB_TOP], 1u);
;             const unsigned tg = og / nx;
;             if (og + 1u == (tg + 1u) * nx) xb_add(&bar[XB_TOPGEN], 1u);
;             else XB_SPIN(xb_ld(&bar[XB_TOPGEN]) == tg, bar);
;             __builtin_amdgcn_fence(__ATOMIC_ACQUIRE, "agent");
;             xb_add(&bar[XB_XGEN(bx_)], 1u);
;             asm volatile("s_waitcnt vmcnt(0)" ::: "memory");
;         } else {
;             XB_SPIN(xb_ld(&bar[XB_XGEN(bx_)]) == gen, bar);
.LBB0_407:
	s_or_b64 exec, exec, s[10:11]
	v_cvt_f32_u32_e32 v7, v5
	s_waitcnt vmcnt(0)
	v_readfirstlane_b32 s1, v6
	v_sub_u32_e32 v6, 0, v5
	v_rcp_iflag_f32_e32 v7, v7
	v_add_u32_e32 v8, s1, v3
	v_mul_f32_e32 v7, 0x4f7ffffe, v7
	v_cvt_u32_f32_e32 v7, v7
	v_mul_lo_u32 v3, v6, v7
	v_mul_hi_u32 v3, v7, v3
	v_add_u32_e32 v3, v7, v3
	v_mul_hi_u32 v3, v8, v3
	v_mul_lo_u32 v6, v3, v5
	v_sub_u32_e32 v6, v8, v6
	v_add_u32_e32 v7, 1, v3
	v_cmp_ge_u32_e32 vcc, v6, v5
	s_nop 1
	v_cndmask_b32_e32 v3, v3, v7, vcc
	v_sub_u32_e32 v7, v6, v5
	v_cndmask_b32_e32 v6, v6, v7, vcc
	v_add_u32_e32 v7, 1, v3
	v_cmp_ge_u32_e32 vcc, v6, v5
	v_add_u32_e32 v6, 1, v8
	s_nop 0
	v_cndmask_b32_e32 v3, v3, v7, vcc
	v_mul_lo_u32 v7, v5, v3
	v_add_u32_e32 v5, v7, v5
	v_cmp_ne_u32_e32 vcc, v6, v5
	s_and_saveexec_b64 s[8:9], vcc
	s_xor_b64 s[8:9], exec, s[8:9]
	s_cbranch_execz .LBB0_421
	s_add_i32 s44, s0, 0x900
	s_lshl_b64 s[10:11], s[44:45], 2
	s_add_u32 s12, s6, 0x3500
	s_addc_u32 s13, s7, 0
	s_waitcnt lgkmcnt(0)
	global_load_dword v4, v201, s[12:13] sc1
	s_waitcnt vmcnt(0)
	v_cmp_eq_u32_e32 vcc, v4, v3
	s_and_saveexec_b64 s[10:11], vcc
	s_cbranch_execz .LBB0_420
	s_mov_b32 s1, 1
	s_mov_b64 s[14:15], 0
	s_branch .LBB0_411

; __device__ __forceinline__ unsigned xb_add(unsigned* p, unsigned v) { return __hip_atomic_fetch_add(p, v, __ATOMIC_RELAXED, __HIP_MEMORY_SCOPE_AGENT); }
; __device__ __forceinline__ void xcd_barrier(const XcdBarrier& b) {
;     ...
;             __builtin_amdgcn_fence(__ATOMIC_ACQUIRE, "agent");
;             xb_add(&bar[XB_XGEN(bx_)], 1u);
;             asm volatile("s_waitcnt vmcnt(0)" ::: "memory");
.LBB0_438:
	s_or_b64 exec, exec, s[8:9]
	s_mov_b64 s[8:9], exec
	v_mbcnt_lo_u32_b32 v3, s8, 0
	v_mbcnt_hi_u32_b32 v3, s9, v3
	v_cmp_eq_u32_e32 vcc, 0, v3
	s_waitcnt vmcnt(0)
	buffer_inv sc1
	s_and_saveexec_b64 s[10:11], vcc
	s_cbranch_execz .LBB0_440
	s_add_i32 s44, s0, 0x900
	s_lshl_b64 s[0:1], s[44:45], 2
	s_add_u32 s0, s6, s0
	s_addc_u32 s1, s7, s1
	s_bcnt1_i32_b64 s6, s[8:9]
	v_mov_b32_e32 v3, s6
.LBB0_440:
	s_or_b64 exec, exec, s[10:11]
	s_waitcnt vmcnt(0)

; __device__ __forceinline__ unsigned xb_ld(unsigned* p)              { return __hip_atomic_load(p, __ATOMIC_RELAXED, __HIP_MEMORY_SCOPE_AGENT); }
; __device__ __forceinline__ unsigned xb_add(unsigned* p, unsigned v) { return __hip_atomic_fetch_add(p, v, __ATOMIC_RELAXED, __HIP_MEMORY_SCOPE_AGENT); }
; #define XB_SPIN(cond, bar) do { unsigned _sp = 0; while (cond) { __builtin_amdgcn_s_sleep(1); \
;     if ((++_sp & 255u) == 0u) { if (xb_ld(&(bar)[XB_TMO])) break; if (_sp > XB_SPIN_CAP) { atomicAdd(&(bar)[XB_TMO], 1u); break; } } } } while (0)
; __device__ __forceinline__ void xcd_barrier(const XcdBarrier& b) {
;     ...
;         const unsigned old = xb_add(&bar[XB_XSUB(bx_)], 1u);
;         const unsigned gen = old / nloc;
;         if (old + 1u == (gen + 1u) * nloc) {
;             __builtin_amdgcn_fence(__ATOMIC_RELEASE, "agent");
;             asm volatile("s_waitcnt vmcnt(0)" ::: "memory");
;             const unsigned og = xb_add(&bar[XB_TOP], 1u);
;             const unsigned tg = og / nx;
;             if (og + 1u == (tg + 1u) * nx) xb_add(&bar[XB_TOPGEN], 1u);
;             else XB_SPIN(xb_ld(&bar[XB_TOPGEN]) == tg, bar);
;             __builtin_amdgcn_fence(__ATOMIC_ACQUIRE, "agent");
;             xb_add(&bar[XB_XGEN(bx_)], 1u);
;             asm volatile("s_waitcnt vmcnt(0)" ::: "memory");
;         } else {
;             XB_SPIN(xb_ld(&bar[XB_XGEN(bx_)]) == gen, bar);
.LBB0_495:
	s_or_b64 exec, exec, s[12:13]
	v_cvt_f32_u32_e32 v7, v5
	s_waitcnt vmcnt(0)
	v_readfirstlane_b32 s4, v6
	v_sub_u32_e32 v6, 0, v5
	v_rcp_iflag_f32_e32 v7, v7
	v_add_u32_e32 v8, s4, v3
	v_mul_f32_e32 v7, 0x4f7ffffe, v7
	v_cvt_u32_f32_e32 v7, v7
	v_mul_lo_u32 v3, v6, v7
	v_mul_hi_u32 v3, v7, v3
	v_add_u32_e32 v3, v7, v3
	v_mul_hi_u32 v3, v8, v3
	v_mul_lo_u32 v6, v3, v5
	v_sub_u32_e32 v6, v8, v6
	v_add_u32_e32 v7, 1, v3
	v_cmp_ge_u32_e32 vcc, v6, v5
	s_nop 1
	v_cndmask_b32_e32 v3, v3, v7, vcc
	v_sub_u32_e32 v7, v6, v5
	v_cndmask_b32_e32 v6, v6, v7, vcc
	v_add_u32_e32 v7, 1, v3
	v_cmp_ge_u32_e32 vcc, v6, v5
	v_add_u32_e32 v6, 1, v8
	s_nop 0
	v_cndmask_b32_e32 v3, v3, v7, vcc
	v_mul_lo_u32 v7, v5, v3
	v_add_u32_e32 v5, v7, v5
	v_cmp_ne_u32_e32 vcc, v6, v5
	s_and_saveexec_b64 s[4:5], vcc
	s_xor_b64 s[10:11], exec, s[4:5]
	s_cbranch_execz .LBB0_509
	s_add_i32 s44, s1, 0x900
	s_lshl_b64 s[4:5], s[44:45], 2
	s_add_u32 s14, s8, 0x3500
	s_addc_u32 s15, s9, 0
	s_waitcnt lgkmcnt(0)
	global_load_dword v4, v201, s[14:15] sc1
	s_waitcnt vmcnt(0)
	v_cmp_eq_u32_e32 vcc, v4, v3
	s_and_saveexec_b64 s[12:13], vcc
	s_cbranch_execz .LBB0_508
	s_mov_b32 s4, 1
	s_mov_b64 s[24:25], 0
	s_branch .LBB0_499

; __device__ __forceinline__ unsigned xb_add(unsigned* p, unsigned v) { return __hip_atomic_fetch_add(p, v, __ATOMIC_RELAXED, __HIP_MEMORY_SCOPE_AGENT); }
; __device__ __forceinline__ void xcd_barrier(const XcdBarrier& b) {
;     ...
;             __builtin_amdgcn_fence(__ATOMIC_ACQUIRE, "agent");
;             xb_add(&bar[XB_XGEN(bx_)], 1u);
;             asm volatile("s_waitcnt vmcnt(0)" ::: "memory");
.LBB0_526:
	s_or_b64 exec, exec, s[10:11]
	s_mov_b64 s[10:11], exec
	v_mbcnt_lo_u32_b32 v3, s10, 0
	v_mbcnt_hi_u32_b32 v3, s11, v3
	v_cmp_eq_u32_e32 vcc, 0, v3
	s_waitcnt vmcnt(0)
	buffer_inv sc1
	s_and_saveexec_b64 s[12:13], vcc
	s_cbranch_execz .LBB0_528
	s_add_i32 s44, s1, 0x900
	s_lshl_b64 s[4:5], s[44:45], 2
	s_add_u32 s4, s8, s4
	s_addc_u32 s5, s9, s5
	s_bcnt1_i32_b64 s1, s[10:11]
	v_mov_b32_e32 v3, s1
.LBB0_528:
	s_or_b64 exec, exec, s[12:13]
	s_waitcnt vmcnt(0)

; __device__ __forceinline__ unsigned xb_ld(unsigned* p)              { return __hip_atomic_load(p, __ATOMIC_RELAXED, __HIP_MEMORY_SCOPE_AGENT); }
; __device__ __forceinline__ unsigned xb_add(unsigned* p, unsigned v) { return __hip_atomic_fetch_add(p, v, __ATOMIC_RELAXED, __HIP_MEMORY_SCOPE_AGENT); }
; #define XB_SPIN(cond, bar) do { unsigned _sp = 0; while (cond) { __builtin_amdgcn_s_sleep(1); \
;     if ((++_sp & 255u) == 0u) { if (xb_ld(&(bar)[XB_TMO])) break; if (_sp > XB_SPIN_CAP) { atomicAdd(&(bar)[XB_TMO], 1u); break; } } } } while (0)
; __device__ __forceinline__ void xcd_barrier(const XcdBarrier& b) {
;     ...
;         const unsigned old = xb_add(&bar[XB_XSUB(bx_)], 1u);
;         const unsigned gen = old / nloc;
;         if (old + 1u == (gen + 1u) * nloc) {
;             __builtin_amdgcn_fence(__ATOMIC_RELEASE, "agent");
;             asm volatile("s_waitcnt vmcnt(0)" ::: "memory");
;             const unsigned og = xb_add(&bar[XB_TOP], 1u);
;             const unsigned tg = og / nx;
;             if (og + 1u == (tg + 1u) * nx) xb_add(&bar[XB_TOPGEN], 1u);
;             else XB_SPIN(xb_ld(&bar[XB_TOPGEN]) == tg, bar);
;             __builtin_amdgcn_fence(__ATOMIC_ACQUIRE, "agent");
;             xb_add(&bar[XB_XGEN(bx_)], 1u);
;             asm volatile("s_waitcnt vmcnt(0)" ::: "memory");
;         } else {
;             XB_SPIN(xb_ld(&bar[XB_XGEN(bx_)]) == gen, bar);
.LBB0_593:
	s_or_b64 exec, exec, s[14:15]
	v_cvt_f32_u32_e32 v7, v5
	s_waitcnt vmcnt(0)
	v_readfirstlane_b32 s1, v6
	v_sub_u32_e32 v6, 0, v5
	v_rcp_iflag_f32_e32 v7, v7
	v_add_u32_e32 v8, s1, v3
	v_mul_f32_e32 v7, 0x4f7ffffe, v7
	v_cvt_u32_f32_e32 v7, v7
	v_mul_lo_u32 v3, v6, v7
	v_mul_hi_u32 v3, v7, v3
	v_add_u32_e32 v3, v7, v3
	v_mul_hi_u32 v3, v8, v3
	v_mul_lo_u32 v6, v3, v5
	v_sub_u32_e32 v6, v8, v6
	v_add_u32_e32 v7, 1, v3
	v_cmp_ge_u32_e32 vcc, v6, v5
	s_nop 1
	v_cndmask_b32_e32 v3, v3, v7, vcc
	v_sub_u32_e32 v7, v6, v5
	v_cndmask_b32_e32 v6, v6, v7, vcc
	v_add_u32_e32 v7, 1, v3
	v_cmp_ge_u32_e32 vcc, v6, v5
	v_add_u32_e32 v6, 1, v8
	s_nop 0
	v_cndmask_b32_e32 v3, v3, v7, vcc
	v_mul_lo_u32 v7, v5, v3
	v_add_u32_e32 v5, v7, v5
	v_cmp_ne_u32_e32 vcc, v6, v5
	s_and_saveexec_b64 s[4:5], vcc
	s_xor_b64 s[12:13], exec, s[4:5]
	s_cbranch_execz .LBB0_607
	s_add_i32 s44, s0, 0x900
	s_lshl_b64 s[4:5], s[44:45], 2
	s_add_u32 s24, s10, 0x3500
	s_addc_u32 s25, s11, 0
	s_waitcnt lgkmcnt(0)
	global_load_dword v4, v201, s[24:25] sc1
	s_waitcnt vmcnt(0)
	v_cmp_eq_u32_e32 vcc, v4, v3
	s_and_saveexec_b64 s[14:15], vcc
	s_cbranch_execz .LBB0_606
	s_mov_b32 s1, 1
	s_mov_b64 s[60:61], 0
	s_branch .LBB0_597

; __device__ __forceinline__ unsigned xb_add(unsigned* p, unsigned v) { return __hip_atomic_fetch_add(p, v, __ATOMIC_RELAXED, __HIP_MEMORY_SCOPE_AGENT); }
; __device__ __forceinline__ void xcd_barrier(const XcdBarrier& b) {
;     ...
;             __builtin_amdgcn_fence(__ATOMIC_ACQUIRE, "agent");
;             xb_add(&bar[XB_XGEN(bx_)], 1u);
;             asm volatile("s_waitcnt vmcnt(0)" ::: "memory");
.LBB0_624:
	s_or_b64 exec, exec, s[12:13]
	s_mov_b64 s[12:13], exec
	v_mbcnt_lo_u32_b32 v3, s12, 0
	v_mbcnt_hi_u32_b32 v3, s13, v3
	v_cmp_eq_u32_e32 vcc, 0, v3
	s_waitcnt vmcnt(0)
	buffer_inv sc1
	s_and_saveexec_b64 s[14:15], vcc
	s_cbranch_execz .LBB0_626
	s_add_i32 s44, s0, 0x900
	s_lshl_b64 s[0:1], s[44:45], 2
	s_add_u32 s0, s10, s0
	s_addc_u32 s1, s11, s1
	s_bcnt1_i32_b64 s4, s[12:13]
	v_mov_b32_e32 v3, s4
.LBB0_626:
	s_or_b64 exec, exec, s[14:15]
	s_waitcnt vmcnt(0)

; __device__ __forceinline__ unsigned xb_ld(unsigned* p)              { return __hip_atomic_load(p, __ATOMIC_RELAXED, __HIP_MEMORY_SCOPE_AGENT); }
; __device__ __forceinline__ unsigned xb_add(unsigned* p, unsigned v) { return __hip_atomic_fetch_add(p, v, __ATOMIC_RELAXED, __HIP_MEMORY_SCOPE_AGENT); }
; #define XB_SPIN(cond, bar) do { unsigned _sp = 0; while (cond) { __builtin_amdgcn_s_sleep(1); \
;     if ((++_sp & 255u) == 0u) { if (xb_ld(&(bar)[XB_TMO])) break; if (_sp > XB_SPIN_CAP) { atomicAdd(&(bar)[XB_TMO], 1u); break; } } } } while (0)
; __device__ __forceinline__ void xcd_barrier(const XcdBarrier& b) {
;     ...
;         const unsigned old = xb_add(&bar[XB_XSUB(bx_)], 1u);
;         const unsigned gen = old / nloc;
;         if (old + 1u == (gen + 1u) * nloc) {
;             __builtin_amdgcn_fence(__ATOMIC_RELEASE, "agent");
;             asm volatile("s_waitcnt vmcnt(0)" ::: "memory");
;             const unsigned og = xb_add(&bar[XB_TOP], 1u);
;             const unsigned tg = og / nx;
;             if (og + 1u == (tg + 1u) * nx) xb_add(&bar[XB_TOPGEN], 1u);
;             else XB_SPIN(xb_ld(&bar[XB_TOPGEN]) == tg, bar);
;             __builtin_amdgcn_fence(__ATOMIC_ACQUIRE, "agent");
;             xb_add(&bar[XB_XGEN(bx_)], 1u);
;             asm volatile("s_waitcnt vmcnt(0)" ::: "memory");
;         } else {
;             XB_SPIN(xb_ld(&bar[XB_XGEN(bx_)]) == gen, bar);
.LBB0_708:
	s_or_b64 exec, exec, s[14:15]
	v_cvt_f32_u32_e32 v7, v5
	s_waitcnt vmcnt(0)
	v_readfirstlane_b32 s4, v6
	v_sub_u32_e32 v6, 0, v5
	v_rcp_iflag_f32_e32 v7, v7
	v_add_u32_e32 v8, s4, v3
	v_mul_f32_e32 v7, 0x4f7ffffe, v7
	v_cvt_u32_f32_e32 v7, v7
	v_mul_lo_u32 v3, v6, v7
	v_mul_hi_u32 v3, v7, v3
	v_add_u32_e32 v3, v7, v3
	v_mul_hi_u32 v3, v8, v3
	v_mul_lo_u32 v6, v3, v5
	v_sub_u32_e32 v6, v8, v6
	v_add_u32_e32 v7, 1, v3
	v_cmp_ge_u32_e32 vcc, v6, v5
	s_nop 1
	v_cndmask_b32_e32 v3, v3, v7, vcc
	v_sub_u32_e32 v7, v6, v5
	v_cndmask_b32_e32 v6, v6, v7, vcc
	v_add_u32_e32 v7, 1, v3
	v_cmp_ge_u32_e32 vcc, v6, v5
	v_add_u32_e32 v6, 1, v8
	s_nop 0
	v_cndmask_b32_e32 v3, v3, v7, vcc
	v_mul_lo_u32 v7, v5, v3
	v_add_u32_e32 v5, v7, v5
	v_cmp_ne_u32_e32 vcc, v6, v5
	s_and_saveexec_b64 s[4:5], vcc
	s_xor_b64 s[12:13], exec, s[4:5]
	s_cbranch_execz .LBB0_722
	s_add_i32 s44, s1, 0x900
	s_lshl_b64 s[4:5], s[44:45], 2
	s_add_u32 s24, s10, 0x3500
	s_addc_u32 s25, s11, 0
	s_waitcnt lgkmcnt(0)
	global_load_dword v4, v201, s[24:25] sc1
	s_waitcnt vmcnt(0)
	v_cmp_eq_u32_e32 vcc, v4, v3
	s_and_saveexec_b64 s[14:15], vcc
	s_cbranch_execz .LBB0_721
	s_mov_b32 s4, 1
	s_mov_b64 s[50:51], 0
	s_branch .LBB0_712

; __device__ __forceinline__ unsigned xb_add(unsigned* p, unsigned v) { return __hip_atomic_fetch_add(p, v, __ATOMIC_RELAXED, __HIP_MEMORY_SCOPE_AGENT); }
; __device__ __forceinline__ void xcd_barrier(const XcdBarrier& b) {
;     ...
;             __builtin_amdgcn_fence(__ATOMIC_ACQUIRE, "agent");
;             xb_add(&bar[XB_XGEN(bx_)], 1u);
;             asm volatile("s_waitcnt vmcnt(0)" ::: "memory");
.LBB0_739:
	s_or_b64 exec, exec, s[12:13]
	s_mov_b64 s[12:13], exec
	v_mbcnt_lo_u32_b32 v3, s12, 0
	v_mbcnt_hi_u32_b32 v3, s13, v3
	v_cmp_eq_u32_e32 vcc, 0, v3
	s_waitcnt vmcnt(0)
	buffer_inv sc1
	s_and_saveexec_b64 s[14:15], vcc
	s_cbranch_execz .LBB0_741
	s_add_i32 s44, s1, 0x900
	s_lshl_b64 s[4:5], s[44:45], 2
	s_add_u32 s4, s10, s4
	s_addc_u32 s5, s11, s5
	s_bcnt1_i32_b64 s1, s[12:13]
	v_mov_b32_e32 v3, s1
.LBB0_741:
	s_or_b64 exec, exec, s[14:15]
	s_waitcnt vmcnt(0)

; __device__ __forceinline__ unsigned xb_add(unsigned* p, unsigned v) { return __hip_atomic_fetch_add(p, v, __ATOMIC_RELAXED, __HIP_MEMORY_SCOPE_AGENT); }
; __device__ __forceinline__ void xcd_barrier(const XcdBarrier& b) {
;     ...
;             __builtin_amdgcn_fence(__ATOMIC_ACQUIRE, "agent");
;             xb_add(&bar[XB_XGEN(bx_)], 1u);
;             asm volatile("s_waitcnt vmcnt(0)" ::: "memory");
.LBB0_813:
	s_or_b64 exec, exec, s[12:13]
	s_mov_b64 s[12:13], exec
	v_mbcnt_lo_u32_b32 v3, s12, 0
	v_mbcnt_hi_u32_b32 v3, s13, v3
	v_cmp_eq_u32_e32 vcc, 0, v3
	s_waitcnt vmcnt(0)
	buffer_inv sc1
	s_and_saveexec_b64 s[14:15], vcc
	s_cbranch_execz .LBB0_815
	s_add_i32 s44, s0, 0x900
	s_lshl_b64 s[0:1], s[44:45], 2
	s_add_u32 s0, s10, s0
	s_addc_u32 s1, s11, s1
	s_bcnt1_i32_b64 s4, s[12:13]
	v_mov_b32_e32 v3, s4
.LBB0_815:
	s_or_b64 exec, exec, s[14:15]
	s_waitcnt vmcnt(0)

; __device__ __forceinline__ unsigned xb_ld(unsigned* p)              { return __hip_atomic_load(p, __ATOMIC_RELAXED, __HIP_MEMORY_SCOPE_AGENT); }
; __device__ __forceinline__ unsigned xb_add(unsigned* p, unsigned v) { return __hip_atomic_fetch_add(p, v, __ATOMIC_RELAXED, __HIP_MEMORY_SCOPE_AGENT); }
; #define XB_SPIN(cond, bar) do { unsigned _sp = 0; while (cond) { __builtin_amdgcn_s_sleep(1); \
;     if ((++_sp & 255u) == 0u) { if (xb_ld(&(bar)[XB_TMO])) break; if (_sp > XB_SPIN_CAP) { atomicAdd(&(bar)[XB_TMO], 1u); break; } } } } while (0)
; __device__ __forceinline__ void xcd_barrier(const XcdBarrier& b) {
;     ...
;         const unsigned old = xb_add(&bar[XB_XSUB(bx_)], 1u);
;         const unsigned gen = old / nloc;
;         if (old + 1u == (gen + 1u) * nloc) {
;             __builtin_amdgcn_fence(__ATOMIC_RELEASE, "agent");
;             asm volatile("s_waitcnt vmcnt(0)" ::: "memory");
;             const unsigned og = xb_add(&bar[XB_TOP], 1u);
;             const unsigned tg = og / nx;
;             if (og + 1u == (tg + 1u) * nx) xb_add(&bar[XB_TOPGEN], 1u);
;             else XB_SPIN(xb_ld(&bar[XB_TOPGEN]) == tg, bar);
;             __builtin_amdgcn_fence(__ATOMIC_ACQUIRE, "agent");
;             xb_add(&bar[XB_XGEN(bx_)], 1u);
;             asm volatile("s_waitcnt vmcnt(0)" ::: "memory");
;         } else {
;             XB_SPIN(xb_ld(&bar[XB_XGEN(bx_)]) == gen, bar);
.LBB0_896:
	s_or_b64 exec, exec, s[24:25]
	v_cvt_f32_u32_e32 v7, v5
	s_waitcnt vmcnt(0)
	v_readfirstlane_b32 s1, v6
	v_sub_u32_e32 v6, 0, v5
	v_rcp_iflag_f32_e32 v7, v7
	v_add_u32_e32 v8, s1, v3
	v_mul_f32_e32 v7, 0x4f7ffffe, v7
	v_cvt_u32_f32_e32 v7, v7
	v_mul_lo_u32 v3, v6, v7
	v_mul_hi_u32 v3, v7, v3
	v_add_u32_e32 v3, v7, v3
	v_mul_hi_u32 v3, v8, v3
	v_mul_lo_u32 v6, v3, v5
	v_sub_u32_e32 v6, v8, v6
	v_add_u32_e32 v7, 1, v3
	v_cmp_ge_u32_e32 vcc, v6, v5
	s_nop 1
	v_cndmask_b32_e32 v3, v3, v7, vcc
	v_sub_u32_e32 v7, v6, v5
	v_cndmask_b32_e32 v6, v6, v7, vcc
	v_add_u32_e32 v7, 1, v3
	v_cmp_ge_u32_e32 vcc, v6, v5
	v_add_u32_e32 v6, 1, v8
	s_nop 0
	v_cndmask_b32_e32 v3, v3, v7, vcc
	v_mul_lo_u32 v7, v5, v3
	v_add_u32_e32 v5, v7, v5
	v_cmp_ne_u32_e32 vcc, v6, v5
	s_and_saveexec_b64 s[4:5], vcc
	s_xor_b64 s[12:13], exec, s[4:5]
	s_cbranch_execz .LBB0_910
	s_add_i32 s44, s0, 0x900
	s_lshl_b64 s[4:5], s[44:45], 2
	s_add_u32 s50, s10, 0x3500
	s_addc_u32 s51, s11, 0
	s_waitcnt lgkmcnt(0)
	global_load_dword v4, v201, s[50:51] sc1
	s_waitcnt vmcnt(0)
	v_cmp_eq_u32_e32 vcc, v4, v3
	s_and_saveexec_b64 s[24:25], vcc
	s_cbranch_execz .LBB0_909
	s_mov_b32 s1, 1
	s_mov_b64 s[60:61], 0
	s_branch .LBB0_900

; __device__ __forceinline__ unsigned xb_add(unsigned* p, unsigned v) { return __hip_atomic_fetch_add(p, v, __ATOMIC_RELAXED, __HIP_MEMORY_SCOPE_AGENT); }
; __device__ __forceinline__ void xcd_barrier(const XcdBarrier& b) {
;     ...
;             __builtin_amdgcn_fence(__ATOMIC_ACQUIRE, "agent");
;             xb_add(&bar[XB_XGEN(bx_)], 1u);
;             asm volatile("s_waitcnt vmcnt(0)" ::: "memory");
.LBB0_927:
	s_or_b64 exec, exec, s[12:13]
	s_mov_b64 s[12:13], exec
	v_mbcnt_lo_u32_b32 v3, s12, 0
	v_mbcnt_hi_u32_b32 v3, s13, v3
	v_cmp_eq_u32_e32 vcc, 0, v3
	s_waitcnt vmcnt(0)
	buffer_inv sc1
	s_and_saveexec_b64 s[24:25], vcc
	s_cbranch_execz .LBB0_929
	s_add_i32 s44, s0, 0x900
	s_lshl_b64 s[0:1], s[44:45], 2
	s_add_u32 s0, s10, s0
	s_addc_u32 s1, s11, s1
	s_bcnt1_i32_b64 s4, s[12:13]
	v_mov_b32_e32 v3, s4
.LBB0_929:
	s_or_b64 exec, exec, s[24:25]
	s_waitcnt vmcnt(0)

; __device__ __forceinline__ unsigned xb_ld(unsigned* p)              { return __hip_atomic_load(p, __ATOMIC_RELAXED, __HIP_MEMORY_SCOPE_AGENT); }
; __device__ __forceinline__ unsigned xb_add(unsigned* p, unsigned v) { return __hip_atomic_fetch_add(p, v, __ATOMIC_RELAXED, __HIP_MEMORY_SCOPE_AGENT); }
; #define XB_SPIN(cond, bar) do { unsigned _sp = 0; while (cond) { __builtin_amdgcn_s_sleep(1); \
;     if ((++_sp & 255u) == 0u) { if (xb_ld(&(bar)[XB_TMO])) break; if (_sp > XB_SPIN_CAP) { atomicAdd(&(bar)[XB_TMO], 1u); break; } } } } while (0)
; __device__ __forceinline__ void xcd_barrier(const XcdBarrier& b) {
;     ...
;         const unsigned old = xb_add(&bar[XB_XSUB(bx_)], 1u);
;         const unsigned gen = old / nloc;
;         if (old + 1u == (gen + 1u) * nloc) {
;             __builtin_amdgcn_fence(__ATOMIC_RELEASE, "agent");
;             asm volatile("s_waitcnt vmcnt(0)" ::: "memory");
;             const unsigned og = xb_add(&bar[XB_TOP], 1u);
;             const unsigned tg = og / nx;
;             if (og + 1u == (tg + 1u) * nx) xb_add(&bar[XB_TOPGEN], 1u);
;             else XB_SPIN(xb_ld(&bar[XB_TOPGEN]) == tg, bar);
;             __builtin_amdgcn_fence(__ATOMIC_ACQUIRE, "agent");
;             xb_add(&bar[XB_XGEN(bx_)], 1u);
;             asm volatile("s_waitcnt vmcnt(0)" ::: "memory");
;         } else {
;             XB_SPIN(xb_ld(&bar[XB_XGEN(bx_)]) == gen, bar);
.LBB0_951:
	s_or_b64 exec, exec, s[14:15]
	v_cvt_f32_u32_e32 v7, v5
	s_waitcnt vmcnt(0)
	v_readfirstlane_b32 s1, v6
	v_sub_u32_e32 v6, 0, v5
	v_rcp_iflag_f32_e32 v7, v7
	v_add_u32_e32 v8, s1, v3
	v_mul_f32_e32 v7, 0x4f7ffffe, v7
	v_cvt_u32_f32_e32 v7, v7
	v_mul_lo_u32 v3, v6, v7
	v_mul_hi_u32 v3, v7, v3
	v_add_u32_e32 v3, v7, v3
	v_mul_hi_u32 v3, v8, v3
	v_mul_lo_u32 v6, v3, v5
	v_sub_u32_e32 v6, v8, v6
	v_add_u32_e32 v7, 1, v3
	v_cmp_ge_u32_e32 vcc, v6, v5
	s_nop 1
	v_cndmask_b32_e32 v3, v3, v7, vcc
	v_sub_u32_e32 v7, v6, v5
	v_cndmask_b32_e32 v6, v6, v7, vcc
	v_add_u32_e32 v7, 1, v3
	v_cmp_ge_u32_e32 vcc, v6, v5
	v_add_u32_e32 v6, 1, v8
	s_nop 0
	v_cndmask_b32_e32 v3, v3, v7, vcc
	v_mul_lo_u32 v7, v5, v3
	v_add_u32_e32 v5, v7, v5
	v_cmp_ne_u32_e32 vcc, v6, v5
	s_and_saveexec_b64 s[4:5], vcc
	s_xor_b64 s[12:13], exec, s[4:5]
	s_cbranch_execz .LBB0_965
	s_add_i32 s44, s0, 0x900
	s_lshl_b64 s[4:5], s[44:45], 2
	s_add_u32 s24, s10, 0x3500
	s_addc_u32 s25, s11, 0
	s_waitcnt lgkmcnt(0)
	global_load_dword v4, v201, s[24:25] sc1
	s_waitcnt vmcnt(0)
	v_cmp_eq_u32_e32 vcc, v4, v3
	s_and_saveexec_b64 s[14:15], vcc
	s_cbranch_execz .LBB0_964
	s_mov_b32 s1, 1
	s_mov_b64 s[50:51], 0
	s_branch .LBB0_955

; __device__ __forceinline__ unsigned xb_add(unsigned* p, unsigned v) { return __hip_atomic_fetch_add(p, v, __ATOMIC_RELAXED, __HIP_MEMORY_SCOPE_AGENT); }
; __device__ __forceinline__ void xcd_barrier(const XcdBarrier& b) {
;     ...
;             __builtin_amdgcn_fence(__ATOMIC_ACQUIRE, "agent");
;             xb_add(&bar[XB_XGEN(bx_)], 1u);
;             asm volatile("s_waitcnt vmcnt(0)" ::: "memory");
.LBB0_982:
	s_or_b64 exec, exec, s[12:13]
	s_mov_b64 s[12:13], exec
	v_mbcnt_lo_u32_b32 v3, s12, 0
	v_mbcnt_hi_u32_b32 v3, s13, v3
	v_cmp_eq_u32_e32 vcc, 0, v3
	s_waitcnt vmcnt(0)
	buffer_inv sc1
	s_and_saveexec_b64 s[14:15], vcc
	s_cbranch_execz .LBB0_984
	s_add_i32 s44, s0, 0x900
	s_lshl_b64 s[0:1], s[44:45], 2
	s_add_u32 s0, s10, s0
	s_addc_u32 s1, s11, s1
	s_bcnt1_i32_b64 s4, s[12:13]
	v_mov_b32_e32 v3, s4
.LBB0_984:
	s_or_b64 exec, exec, s[14:15]
	s_waitcnt vmcnt(0)

; __device__ __forceinline__ unsigned xb_add(unsigned* p, unsigned v) { return __hip_atomic_fetch_add(p, v, __ATOMIC_RELAXED, __HIP_MEMORY_SCOPE_AGENT); }
; __device__ __forceinline__ void xcd_barrier(const XcdBarrier& b) {
;     ...
;             __builtin_amdgcn_fence(__ATOMIC_ACQUIRE, "agent");
;             xb_add(&bar[XB_XGEN(bx_)], 1u);
;             asm volatile("s_waitcnt vmcnt(0)" ::: "memory");
.LBB0_1070:
	s_or_b64 exec, exec, s[12:13]
	s_mov_b64 s[12:13], exec
	v_mbcnt_lo_u32_b32 v3, s12, 0
	v_mbcnt_hi_u32_b32 v3, s13, v3
	v_cmp_eq_u32_e32 vcc, 0, v3
	s_waitcnt vmcnt(0)
	buffer_inv sc1
	s_and_saveexec_b64 s[14:15], vcc
	s_cbranch_execz .LBB0_1072
	s_add_i32 s44, s1, 0x900
	s_lshl_b64 s[4:5], s[44:45], 2
	s_add_u32 s4, s10, s4
	s_addc_u32 s5, s11, s5
	s_bcnt1_i32_b64 s1, s[12:13]
	v_mov_b32_e32 v3, s1
.LBB0_1072:
	s_or_b64 exec, exec, s[14:15]
	s_waitcnt vmcnt(0)

; __device__ __forceinline__ unsigned xb_ld(unsigned* p)              { return __hip_atomic_load(p, __ATOMIC_RELAXED, __HIP_MEMORY_SCOPE_AGENT); }
; __device__ __forceinline__ unsigned xb_add(unsigned* p, unsigned v) { return __hip_atomic_fetch_add(p, v, __ATOMIC_RELAXED, __HIP_MEMORY_SCOPE_AGENT); }
; #define XB_SPIN(cond, bar) do { unsigned _sp = 0; while (cond) { __builtin_amdgcn_s_sleep(1); \
;     if ((++_sp & 255u) == 0u) { if (xb_ld(&(bar)[XB_TMO])) break; if (_sp > XB_SPIN_CAP) { atomicAdd(&(bar)[XB_TMO], 1u); break; } } } } while (0)
; __device__ __forceinline__ void xcd_barrier(const XcdBarrier& b) {
;     ...
;         const unsigned old = xb_add(&bar[XB_XSUB(bx_)], 1u);
;         const unsigned gen = old / nloc;
;         if (old + 1u == (gen + 1u) * nloc) {
;             __builtin_amdgcn_fence(__ATOMIC_RELEASE, "agent");
;             asm volatile("s_waitcnt vmcnt(0)" ::: "memory");
;             const unsigned og = xb_add(&bar[XB_TOP], 1u);
;             const unsigned tg = og / nx;
;             if (og + 1u == (tg + 1u) * nx) xb_add(&bar[XB_TOPGEN], 1u);
;             else XB_SPIN(xb_ld(&bar[XB_TOPGEN]) == tg, bar);
;             __builtin_amdgcn_fence(__ATOMIC_ACQUIRE, "agent");
;             xb_add(&bar[XB_XGEN(bx_)], 1u);
;             asm volatile("s_waitcnt vmcnt(0)" ::: "memory");
;         } else {
;             XB_SPIN(xb_ld(&bar[XB_XGEN(bx_)]) == gen, bar);
.LBB0_1137:
	s_or_b64 exec, exec, s[12:13]
	v_cvt_f32_u32_e32 v7, v5
	s_waitcnt vmcnt(0)
	v_readfirstlane_b32 s1, v6
	v_sub_u32_e32 v6, 0, v5
	v_rcp_iflag_f32_e32 v7, v7
	v_add_u32_e32 v8, s1, v3
	v_mul_f32_e32 v7, 0x4f7ffffe, v7
	v_cvt_u32_f32_e32 v7, v7
	v_mul_lo_u32 v3, v6, v7
	v_mul_hi_u32 v3, v7, v3
	v_add_u32_e32 v3, v7, v3
	v_mul_hi_u32 v3, v8, v3
	v_mul_lo_u32 v6, v3, v5
	v_sub_u32_e32 v6, v8, v6
	v_add_u32_e32 v7, 1, v3
	v_cmp_ge_u32_e32 vcc, v6, v5
	s_nop 1
	v_cndmask_b32_e32 v3, v3, v7, vcc
	v_sub_u32_e32 v7, v6, v5
	v_cndmask_b32_e32 v6, v6, v7, vcc
	v_add_u32_e32 v7, 1, v3
	v_cmp_ge_u32_e32 vcc, v6, v5
	v_add_u32_e32 v6, 1, v8
	s_nop 0
	v_cndmask_b32_e32 v3, v3, v7, vcc
	v_mul_lo_u32 v7, v5, v3
	v_add_u32_e32 v5, v7, v5
	v_cmp_ne_u32_e32 vcc, v6, v5
	s_and_saveexec_b64 s[4:5], vcc
	s_xor_b64 s[10:11], exec, s[4:5]
	s_cbranch_execz .LBB0_1151
	s_add_i32 s44, s0, 0x900
	s_lshl_b64 s[4:5], s[44:45], 2
	s_add_u32 s24, s8, 0x3500
	s_addc_u32 s25, s9, 0
	s_waitcnt lgkmcnt(0)
	global_load_dword v4, v201, s[24:25] sc1
	s_waitcnt vmcnt(0)
	v_cmp_eq_u32_e32 vcc, v4, v3
	s_and_saveexec_b64 s[12:13], vcc
	s_cbranch_execz .LBB0_1150
	s_mov_b32 s1, 1
	s_mov_b64 s[60:61], 0
	s_branch .LBB0_1141

; __device__ __forceinline__ unsigned xb_add(unsigned* p, unsigned v) { return __hip_atomic_fetch_add(p, v, __ATOMIC_RELAXED, __HIP_MEMORY_SCOPE_AGENT); }
; __device__ __forceinline__ void xcd_barrier(const XcdBarrier& b) {
;     ...
;             __builtin_amdgcn_fence(__ATOMIC_ACQUIRE, "agent");
;             xb_add(&bar[XB_XGEN(bx_)], 1u);
;             asm volatile("s_waitcnt vmcnt(0)" ::: "memory");
.LBB0_1168:
	s_or_b64 exec, exec, s[10:11]
	s_mov_b64 s[10:11], exec
	v_mbcnt_lo_u32_b32 v3, s10, 0
	v_mbcnt_hi_u32_b32 v3, s11, v3
	v_cmp_eq_u32_e32 vcc, 0, v3
	s_waitcnt vmcnt(0)
	buffer_inv sc1
	s_and_saveexec_b64 s[12:13], vcc
	s_cbranch_execz .LBB0_1170
	s_add_i32 s44, s0, 0x900
	s_lshl_b64 s[0:1], s[44:45], 2
	s_add_u32 s0, s8, s0
	s_addc_u32 s1, s9, s1
	s_bcnt1_i32_b64 s4, s[10:11]
	v_mov_b32_e32 v3, s4
.LBB0_1170:
	s_or_b64 exec, exec, s[12:13]
	s_waitcnt vmcnt(0)

; __device__ __forceinline__ unsigned xb_add(unsigned* p, unsigned v) { return __hip_atomic_fetch_add(p, v, __ATOMIC_RELAXED, __HIP_MEMORY_SCOPE_AGENT); }
; __device__ __forceinline__ void xcd_barrier(const XcdBarrier& b) {
;     ...
;             __builtin_amdgcn_fence(__ATOMIC_ACQUIRE, "agent");
;             xb_add(&bar[XB_XGEN(bx_)], 1u);
;             asm volatile("s_waitcnt vmcnt(0)" ::: "memory");
.LBB0_1327:
	s_add_i32 s44, s0, 0x900
	s_lshl_b64 s[0:1], s[44:45], 2
	s_add_u32 s0, s6, s0
	s_addc_u32 s1, s7, s1
	s_bcnt1_i32_b64 s6, s[8:9]
	v_mov_b32_e32 v3, s6
	s_getpc_b64 s[98:99]
